# trailing wave half computes the next-tile schedule before its offset-restoring barrier (was after): overlaps with the leading half's first load segment
# baseline (speedup 1.0000x reference)
; #define PG8_BAR __builtin_amdgcn_s_barrier()
; __device__ __forceinline__ void gemm_phase(const Ctx& cx, LAS unsigned char* lds, const GemmDesc& g) {
;     ...
;     cur = nxt; cA1 = nA1; cA2 = nA2; cB = nB; aoffu = naoff; ++ui;
;     if (wr == 1) PG8_BAR;
.LBB0_357:
	s_cmp_eq_u32 s98, 0
	s_cbranch_scc1 .Lrb_skip
	s_mov_b32 s98, 0
	v_readlane_b32 s6, v255, 13
	v_readlane_b32 s7, v255, 14
	s_andn2_b64 vcc, exec, s[6:7]
	s_cbranch_vccnz .Lrb_skip
	s_barrier

; #define PG8_BAR __builtin_amdgcn_s_barrier()
; __device__ __forceinline__ void gemm_phase(const Ctx& cx, LAS unsigned char* lds, const GemmDesc& g) {
;     ...
;     if (wr == 1) PG8_BAR;
.LBB0_509:
	v_readlane_b32 s4, v255, 13
	v_readlane_b32 s5, v255, 14
	s_andn2_b64 vcc, exec, s[4:5]
	s_cbranch_vccnz .LBB0_349
	s_branch .LBB0_349
